# conv units: nt cache policy on the once-read f32 weight loads and once-written bf16 stores; on top of v29
# speedup vs baseline: 1.0113x; 1.0110x over previous
.Lcv_d_p:
	s_sub_i32 s45, s43, 6
	s_lshr_b32 s47, s41, s45
	s_bfm_b32 s84, s45, 0
	s_and_b32 s84, s41, s84
	s_add_i32 s45, s43, 8
	s_lshl_b32 s47, s47, s45
	s_lshl_b32 s84, s84, 8
	s_add_u32 s47, s47, s84
	s_add_u32 s10, s10, s47
	s_addc_u32 s11, s11, 0
	s_add_i32 s45, s43, 2
	v_and_b32_e32 v165, 63, v0
	v_lshrrev_b32_e32 v164, 4, v165
	v_and_b32_e32 v165, 15, v165
	v_lshlrev_b32_e32 v164, s45, v164
	v_lshl_add_u32 v164, v165, 4, v164
	s_add_i32 s45, s43, 4
	s_lshl_b32 s47, 1, s45
	global_load_dwordx4 v[100:103], v164, s[10:11] nt
	s_add_u32 s10, s10, s47
	s_addc_u32 s11, s11, 0
	global_load_dwordx4 v[104:107], v164, s[10:11] nt
	s_add_u32 s10, s10, s47
	s_addc_u32 s11, s11, 0
	global_load_dwordx4 v[108:111], v164, s[10:11] nt
	s_add_u32 s10, s10, s47
	s_addc_u32 s11, s11, 0
	global_load_dwordx4 v[112:115], v164, s[10:11] nt
	s_add_u32 s10, s10, s47
	s_addc_u32 s11, s11, 0
	global_load_dwordx4 v[116:119], v164, s[10:11] nt
	s_add_u32 s10, s10, s47
	s_addc_u32 s11, s11, 0
	global_load_dwordx4 v[120:123], v164, s[10:11] nt
	s_add_u32 s10, s10, s47
	s_addc_u32 s11, s11, 0
	global_load_dwordx4 v[124:127], v164, s[10:11] nt
	s_add_u32 s10, s10, s47
	s_addc_u32 s11, s11, 0
	global_load_dwordx4 v[128:131], v164, s[10:11] nt
	s_add_u32 s10, s10, s47
	s_addc_u32 s11, s11, 0
	global_load_dwordx4 v[132:135], v164, s[10:11] nt
	s_add_u32 s10, s10, s47
	s_addc_u32 s11, s11, 0
	global_load_dwordx4 v[136:139], v164, s[10:11] nt
	s_add_u32 s10, s10, s47
	s_addc_u32 s11, s11, 0
	global_load_dwordx4 v[140:143], v164, s[10:11] nt
	s_add_u32 s10, s10, s47
	s_addc_u32 s11, s11, 0
	global_load_dwordx4 v[144:147], v164, s[10:11] nt
	s_add_u32 s10, s10, s47
	s_addc_u32 s11, s11, 0
	global_load_dwordx4 v[148:151], v164, s[10:11] nt
	s_add_u32 s10, s10, s47
	s_addc_u32 s11, s11, 0
	global_load_dwordx4 v[152:155], v164, s[10:11] nt
	s_add_u32 s10, s10, s47
	s_addc_u32 s11, s11, 0
	global_load_dwordx4 v[156:159], v164, s[10:11] nt
	s_add_u32 s10, s10, s47
	s_addc_u32 s11, s11, 0
	global_load_dwordx4 v[160:163], v164, s[10:11] nt
	s_branch .LBB0_360

.Lcv_d_a:
	s_sub_i32 s45, s43, 6
	s_lshr_b32 s47, s41, s45
	s_bfm_b32 s84, s45, 0
	s_and_b32 s84, s41, s84
	s_add_i32 s45, s43, 8
	s_lshl_b32 s47, s47, s45
	s_lshl_b32 s84, s84, 8
	s_add_u32 s47, s47, s84
	s_add_u32 s10, s10, s47
	s_addc_u32 s11, s11, 0
	s_add_i32 s45, s43, 2
	v_and_b32_e32 v165, 63, v0
	v_lshrrev_b32_e32 v164, 4, v165
	v_and_b32_e32 v165, 15, v165
	v_lshlrev_b32_e32 v164, s45, v164
	v_lshl_add_u32 v164, v165, 4, v164
	s_add_i32 s45, s43, 4
	s_lshl_b32 s47, 1, s45
	global_load_dwordx4 v[100:103], v164, s[10:11] nt
	s_add_u32 s10, s10, s47
	s_addc_u32 s11, s11, 0
	global_load_dwordx4 v[104:107], v164, s[10:11] nt
	s_add_u32 s10, s10, s47
	s_addc_u32 s11, s11, 0
	global_load_dwordx4 v[108:111], v164, s[10:11] nt
	s_add_u32 s10, s10, s47
	s_addc_u32 s11, s11, 0
	global_load_dwordx4 v[112:115], v164, s[10:11] nt
	s_add_u32 s10, s10, s47
	s_addc_u32 s11, s11, 0
	global_load_dwordx4 v[116:119], v164, s[10:11] nt
	s_add_u32 s10, s10, s47
	s_addc_u32 s11, s11, 0
	global_load_dwordx4 v[120:123], v164, s[10:11] nt
	s_add_u32 s10, s10, s47
	s_addc_u32 s11, s11, 0
	global_load_dwordx4 v[124:127], v164, s[10:11] nt
	s_add_u32 s10, s10, s47
	s_addc_u32 s11, s11, 0
	global_load_dwordx4 v[128:131], v164, s[10:11] nt
	s_add_u32 s10, s10, s47
	s_addc_u32 s11, s11, 0
	global_load_dwordx4 v[132:135], v164, s[10:11] nt
	s_add_u32 s10, s10, s47
	s_addc_u32 s11, s11, 0
	global_load_dwordx4 v[136:139], v164, s[10:11] nt
	s_add_u32 s10, s10, s47
	s_addc_u32 s11, s11, 0
	global_load_dwordx4 v[140:143], v164, s[10:11] nt
	s_add_u32 s10, s10, s47
	s_addc_u32 s11, s11, 0
	global_load_dwordx4 v[144:147], v164, s[10:11] nt
	s_add_u32 s10, s10, s47
	s_addc_u32 s11, s11, 0
	global_load_dwordx4 v[148:151], v164, s[10:11] nt
	s_add_u32 s10, s10, s47
	s_addc_u32 s11, s11, 0
	global_load_dwordx4 v[152:155], v164, s[10:11] nt
	s_add_u32 s10, s10, s47
	s_addc_u32 s11, s11, 0
	global_load_dwordx4 v[156:159], v164, s[10:11] nt
	s_add_u32 s10, s10, s47
	s_addc_u32 s11, s11, 0
	global_load_dwordx4 v[160:163], v164, s[10:11] nt
.Lcv_nopf_a:
	s_cmp_lg_u32 s86, 0
	ds_write2_b32 v5, v20, v21 offset1:1
	ds_write2_b32 v5, v22, v23 offset0:2 offset1:3
	ds_write2_b32 v8, v24, v25 offset1:1
	v_add_u32_e32 v8, 0x418, v5
	ds_write2_b32 v8, v26, v27 offset1:1
	v_add_u32_e32 v8, 0x820, v5
	v_mov_b32_e32 v9, v2
	ds_write2_b32 v8, v28, v29 offset1:1
	v_add_u32_e32 v8, 0x828, v5
	ds_write2_b32 v8, v30, v31 offset1:1
	v_add_u32_e32 v8, 0xc30, v5
	ds_write2_b32 v8, v32, v33 offset1:1
	v_add_u32_e32 v8, 0xc38, v5
	ds_write2_b32 v8, v34, v35 offset1:1
	v_add_u32_e32 v8, 0x1040, v5
	ds_write2_b32 v8, v36, v37 offset1:1
	v_add_u32_e32 v8, 0x1048, v5
	ds_write2_b32 v8, v38, v39 offset1:1
	v_add_u32_e32 v8, 0x1450, v5
	ds_write2_b32 v8, v40, v41 offset1:1
	v_add_u32_e32 v8, 0x1458, v5
	ds_write2_b32 v8, v42, v43 offset1:1
	v_add_u32_e32 v8, 0x1860, v5
	v_add_u32_e32 v42, 0x400, v10
	v_mov_b32_e32 v41, v2
	ds_write2_b32 v8, v44, v45 offset1:1
	v_add_u32_e32 v8, 0x1868, v5
	ds_write2_b32 v8, v46, v47 offset1:1
	v_add_u32_e32 v8, 0x1c70, v5
	ds_write2_b32 v8, v48, v49 offset1:1
	v_add_u32_e32 v8, 0x1c78, v5
	ds_write2_b32 v8, v50, v51 offset1:1
	v_add_u32_e32 v8, 0x2080, v5
	ds_write2_b32 v8, v52, v53 offset1:1
	v_add_u32_e32 v8, 0x2088, v5
	ds_write2_b32 v8, v54, v55 offset1:1
	v_add_u32_e32 v8, 0x2490, v5
	ds_write2_b32 v8, v56, v57 offset1:1
	v_add_u32_e32 v8, 0x2498, v5
	ds_write2_b32 v8, v58, v59 offset1:1
	v_add_u32_e32 v8, 0x28a0, v5
	ds_write2_b32 v8, v60, v61 offset1:1
	v_add_u32_e32 v8, 0x28a8, v5
	ds_write2_b32 v8, v62, v63 offset1:1
	v_add_u32_e32 v8, 0x2cb0, v5
	ds_write2_b32 v8, v64, v65 offset1:1
	v_add_u32_e32 v8, 0x2cb8, v5
	ds_write2_b32 v8, v66, v67 offset1:1
	v_add_u32_e32 v8, 0x30c0, v5
	ds_write2_b32 v8, v68, v69 offset1:1
	v_add_u32_e32 v8, 0x30c8, v5
	ds_write2_b32 v8, v70, v71 offset1:1
	v_add_u32_e32 v8, 0x34d0, v5
	ds_write2_b32 v8, v72, v73 offset1:1
	v_add_u32_e32 v8, 0x34d8, v5
	ds_write2_b32 v8, v74, v75 offset1:1
	v_add_u32_e32 v8, 0x38e0, v5
	ds_write2_b32 v8, v76, v77 offset1:1
	v_add_u32_e32 v8, 0x38e8, v5
	ds_write2_b32 v8, v78, v79 offset1:1
	v_add_u32_e32 v8, 0x3cf0, v5
	ds_write2_b32 v8, v80, v81 offset1:1
	v_add_u32_e32 v8, 0x3cf8, v5
	ds_write2_b32 v8, v82, v83 offset1:1
	s_waitcnt lgkmcnt(0)
	ds_read2_b32 v[24:25], v10 offset1:8
	ds_read2_b32 v[26:27], v10 offset0:65 offset1:73
	ds_read2_b32 v[28:29], v10 offset0:130 offset1:138
	ds_read2_b32 v[30:31], v10 offset0:195 offset1:203
	ds_read2_b32 v[32:33], v42 offset0:4 offset1:12
	s_waitcnt lgkmcnt(4)
	v_bfe_u32 v19, v24, 16, 1
	v_add3_u32 v19, v24, v19, s87
	s_waitcnt lgkmcnt(3)
	v_bfe_u32 v20, v26, 16, 1
	v_lshrrev_b32_e32 v19, 16, v19
	v_add3_u32 v20, v26, v20, s87
	ds_read2_b32 v[34:35], v42 offset0:69 offset1:77
	v_and_or_b32 v20, v20, s90, v19
	s_waitcnt lgkmcnt(3)
	v_bfe_u32 v19, v28, 16, 1
	v_add3_u32 v19, v28, v19, s87
	s_waitcnt lgkmcnt(2)
	v_bfe_u32 v21, v30, 16, 1
	ds_read2_b32 v[36:37], v42 offset0:134 offset1:142
	v_lshrrev_b32_e32 v19, 16, v19
	v_add3_u32 v21, v30, v21, s87
	ds_read2_b32 v[38:39], v42 offset0:199 offset1:207
	v_and_or_b32 v21, v21, s90, v19
	s_waitcnt lgkmcnt(3)
	v_bfe_u32 v19, v32, 16, 1
	v_add3_u32 v19, v32, v19, s87
	s_waitcnt lgkmcnt(2)
	v_bfe_u32 v22, v34, 16, 1
	v_lshrrev_b32_e32 v19, 16, v19
	v_add3_u32 v22, v34, v22, s87
	v_and_or_b32 v22, v22, s90, v19
	s_waitcnt lgkmcnt(1)
	v_bfe_u32 v19, v36, 16, 1
	v_add3_u32 v19, v36, v19, s87
	s_waitcnt lgkmcnt(0)
	v_bfe_u32 v23, v38, 16, 1
	v_lshlrev_b32_e32 v8, 1, v6
	v_lshrrev_b32_e32 v19, 16, v19
	v_add3_u32 v23, v38, v23, s87
	v_lshl_add_u64 v[8:9], s[6:7], 0, v[8:9]
	s_mov_b64 s[6:7], 0x10400000
	v_and_or_b32 v23, v23, s90, v19
	v_or_b32_e32 v19, s4, v7
	v_lshl_add_u64 v[8:9], v[8:9], 0, s[6:7]
	v_lshlrev_b32_e32 v40, 7, v19
	v_lshl_add_u64 v[40:41], v[8:9], 0, v[40:41]
	v_bfe_u32 v19, v25, 16, 1
	global_store_dwordx4 v[40:41], v[20:23], off nt
	v_add3_u32 v19, v25, v19, s87
	v_lshrrev_b32_e32 v19, 16, v19
	v_bfe_u32 v20, v27, 16, 1
	v_add3_u32 v20, v27, v20, s87
	v_and_or_b32 v20, v20, s90, v19
	v_bfe_u32 v19, v29, 16, 1
	v_add3_u32 v19, v29, v19, s87
	v_bfe_u32 v21, v31, 16, 1
	v_lshrrev_b32_e32 v19, 16, v19
	v_add3_u32 v21, v31, v21, s87
	v_and_or_b32 v21, v21, s90, v19
	v_bfe_u32 v19, v33, 16, 1
	v_add3_u32 v19, v33, v19, s87
	v_bfe_u32 v22, v35, 16, 1
	v_lshrrev_b32_e32 v19, 16, v19
	v_add3_u32 v22, v35, v22, s87
	v_and_or_b32 v22, v22, s90, v19
	v_bfe_u32 v19, v37, 16, 1
	v_add3_u32 v19, v37, v19, s87
	v_bfe_u32 v23, v39, 16, 1
	v_lshrrev_b32_e32 v19, 16, v19
	v_add3_u32 v23, v39, v23, s87
	v_and_or_b32 v23, v23, s90, v19
	v_or_b32_e32 v19, s4, v11
	v_lshlrev_b32_e32 v24, 7, v19
	v_mov_b32_e32 v25, v2
	ds_read2_b32 v[26:27], v10 offset0:16 offset1:24
	v_lshl_add_u64 v[24:25], v[8:9], 0, v[24:25]
	global_store_dwordx4 v[24:25], v[20:23], off nt
	ds_read2_b32 v[24:25], v10 offset0:81 offset1:89
	ds_read2_b32 v[28:29], v10 offset0:146 offset1:154
	ds_read2_b32 v[30:31], v10 offset0:211 offset1:219
	s_waitcnt lgkmcnt(3)
	v_bfe_u32 v19, v26, 16, 1
	v_add3_u32 v19, v26, v19, s87
	s_waitcnt lgkmcnt(2)
	v_bfe_u32 v20, v24, 16, 1
	ds_read2_b32 v[32:33], v42 offset0:20 offset1:28
	v_lshrrev_b32_e32 v19, 16, v19
	v_add3_u32 v20, v24, v20, s87
	ds_read2_b32 v[34:35], v42 offset0:85 offset1:93
	v_and_or_b32 v20, v20, s90, v19
	s_waitcnt lgkmcnt(3)
	v_bfe_u32 v19, v28, 16, 1
	v_add3_u32 v19, v28, v19, s87
	s_waitcnt lgkmcnt(2)
	v_bfe_u32 v21, v30, 16, 1
	ds_read2_b32 v[36:37], v42 offset0:150 offset1:158
	v_lshrrev_b32_e32 v19, 16, v19
	v_add3_u32 v21, v30, v21, s87
	ds_read2_b32 v[38:39], v42 offset0:215 offset1:223
	v_and_or_b32 v21, v21, s90, v19
	s_waitcnt lgkmcnt(3)
	v_bfe_u32 v19, v32, 16, 1
	v_add3_u32 v19, v32, v19, s87
	s_waitcnt lgkmcnt(2)
	v_bfe_u32 v22, v34, 16, 1
	v_lshrrev_b32_e32 v19, 16, v19
	v_add3_u32 v22, v34, v22, s87
	v_and_or_b32 v22, v22, s90, v19
	s_waitcnt lgkmcnt(1)
	v_bfe_u32 v19, v36, 16, 1
	v_add3_u32 v19, v36, v19, s87
	s_waitcnt lgkmcnt(0)
	v_bfe_u32 v23, v38, 16, 1
	v_lshrrev_b32_e32 v19, 16, v19
	v_add3_u32 v23, v38, v23, s87
	v_and_or_b32 v23, v23, s90, v19
	v_or_b32_e32 v19, s4, v12
	v_lshlrev_b32_e32 v40, 7, v19
	v_mov_b32_e32 v41, v2
	v_lshl_add_u64 v[40:41], v[8:9], 0, v[40:41]
	v_bfe_u32 v19, v27, 16, 1
	global_store_dwordx4 v[40:41], v[20:23], off nt
	v_add3_u32 v19, v27, v19, s87
	v_lshrrev_b32_e32 v19, 16, v19
	v_bfe_u32 v20, v25, 16, 1
	v_add3_u32 v20, v25, v20, s87
	v_and_or_b32 v20, v20, s90, v19
	v_bfe_u32 v19, v29, 16, 1
	v_add3_u32 v19, v29, v19, s87
	v_bfe_u32 v21, v31, 16, 1
	v_lshrrev_b32_e32 v19, 16, v19
	v_add3_u32 v21, v31, v21, s87
	v_and_or_b32 v21, v21, s90, v19
	v_bfe_u32 v19, v33, 16, 1
	v_add3_u32 v19, v33, v19, s87
	v_bfe_u32 v22, v35, 16, 1
	v_lshrrev_b32_e32 v19, 16, v19
	v_add3_u32 v22, v35, v22, s87
	v_and_or_b32 v22, v22, s90, v19
	v_bfe_u32 v19, v37, 16, 1
	v_add3_u32 v19, v37, v19, s87
	v_bfe_u32 v23, v39, 16, 1
	v_lshrrev_b32_e32 v19, 16, v19
	v_add3_u32 v23, v39, v23, s87
	v_and_or_b32 v23, v23, s90, v19
	v_or_b32_e32 v19, s4, v13
	v_lshlrev_b32_e32 v24, 7, v19
	v_mov_b32_e32 v25, v2
	ds_read2_b32 v[26:27], v10 offset0:32 offset1:40
	v_lshl_add_u64 v[24:25], v[8:9], 0, v[24:25]
	global_store_dwordx4 v[24:25], v[20:23], off nt
	ds_read2_b32 v[24:25], v10 offset0:97 offset1:105
	ds_read2_b32 v[28:29], v10 offset0:162 offset1:170
	ds_read2_b32 v[30:31], v10 offset0:227 offset1:235
	s_waitcnt lgkmcnt(3)
	v_bfe_u32 v19, v26, 16, 1
	v_add3_u32 v19, v26, v19, s87
	s_waitcnt lgkmcnt(2)
	v_bfe_u32 v20, v24, 16, 1
	ds_read2_b32 v[32:33], v42 offset0:36 offset1:44
	v_lshrrev_b32_e32 v19, 16, v19
	v_add3_u32 v20, v24, v20, s87
	ds_read2_b32 v[34:35], v42 offset0:101 offset1:109
	v_and_or_b32 v20, v20, s90, v19
	s_waitcnt lgkmcnt(3)
	v_bfe_u32 v19, v28, 16, 1
	v_add3_u32 v19, v28, v19, s87
	s_waitcnt lgkmcnt(2)
	v_bfe_u32 v21, v30, 16, 1
	ds_read2_b32 v[36:37], v42 offset0:166 offset1:174
	v_lshrrev_b32_e32 v19, 16, v19
	v_add3_u32 v21, v30, v21, s87
	ds_read2_b32 v[38:39], v42 offset0:231 offset1:239
	v_and_or_b32 v21, v21, s90, v19
	s_waitcnt lgkmcnt(3)
	v_bfe_u32 v19, v32, 16, 1
	v_add3_u32 v19, v32, v19, s87
	s_waitcnt lgkmcnt(2)
	v_bfe_u32 v22, v34, 16, 1
	v_lshrrev_b32_e32 v19, 16, v19
	v_add3_u32 v22, v34, v22, s87
	v_and_or_b32 v22, v22, s90, v19
	s_waitcnt lgkmcnt(1)
	v_bfe_u32 v19, v36, 16, 1
	v_add3_u32 v19, v36, v19, s87
	s_waitcnt lgkmcnt(0)
	v_bfe_u32 v23, v38, 16, 1
	v_lshrrev_b32_e32 v19, 16, v19
	v_add3_u32 v23, v38, v23, s87
	v_and_or_b32 v23, v23, s90, v19
	v_or_b32_e32 v19, s4, v14
	v_lshlrev_b32_e32 v40, 7, v19
	v_mov_b32_e32 v41, v2
	v_lshl_add_u64 v[40:41], v[8:9], 0, v[40:41]
	v_bfe_u32 v19, v27, 16, 1
	global_store_dwordx4 v[40:41], v[20:23], off nt
	v_add3_u32 v19, v27, v19, s87
	v_lshrrev_b32_e32 v19, 16, v19
	v_bfe_u32 v20, v25, 16, 1
	v_add3_u32 v20, v25, v20, s87
	v_and_or_b32 v20, v20, s90, v19
	v_bfe_u32 v19, v29, 16, 1
	v_add3_u32 v19, v29, v19, s87
	v_bfe_u32 v21, v31, 16, 1
	v_lshrrev_b32_e32 v19, 16, v19
	v_add3_u32 v21, v31, v21, s87
	v_and_or_b32 v21, v21, s90, v19
	v_bfe_u32 v19, v33, 16, 1
	v_add3_u32 v19, v33, v19, s87
	v_bfe_u32 v22, v35, 16, 1
	v_lshrrev_b32_e32 v19, 16, v19
	v_add3_u32 v22, v35, v22, s87
	v_and_or_b32 v22, v22, s90, v19
	v_bfe_u32 v19, v37, 16, 1
	v_add3_u32 v19, v37, v19, s87
	v_bfe_u32 v23, v39, 16, 1
	v_lshrrev_b32_e32 v19, 16, v19
	v_add3_u32 v23, v39, v23, s87
	v_and_or_b32 v23, v23, s90, v19
	v_or_b32_e32 v19, s4, v15
	v_lshlrev_b32_e32 v24, 7, v19
	v_mov_b32_e32 v25, v2
	ds_read2_b32 v[26:27], v10 offset0:48 offset1:56
	v_lshl_add_u64 v[24:25], v[8:9], 0, v[24:25]
	global_store_dwordx4 v[24:25], v[20:23], off nt
	ds_read2_b32 v[24:25], v10 offset0:113 offset1:121
	ds_read2_b32 v[28:29], v10 offset0:178 offset1:186
	ds_read2_b32 v[30:31], v10 offset0:243 offset1:251
	s_waitcnt lgkmcnt(3)
	v_bfe_u32 v19, v26, 16, 1
	v_add3_u32 v19, v26, v19, s87
	s_waitcnt lgkmcnt(2)
	v_bfe_u32 v20, v24, 16, 1
	ds_read2_b32 v[32:33], v42 offset0:52 offset1:60
	v_lshrrev_b32_e32 v19, 16, v19
	v_add3_u32 v20, v24, v20, s87
	ds_read2_b32 v[34:35], v42 offset0:117 offset1:125
	v_and_or_b32 v20, v20, s90, v19
	s_waitcnt lgkmcnt(3)
	v_bfe_u32 v19, v28, 16, 1
	v_add3_u32 v19, v28, v19, s87
	s_waitcnt lgkmcnt(2)
	v_bfe_u32 v21, v30, 16, 1
	ds_read2_b32 v[36:37], v42 offset0:182 offset1:190
	v_lshrrev_b32_e32 v19, 16, v19
	v_add3_u32 v21, v30, v21, s87
	ds_read2_b32 v[38:39], v42 offset0:247 offset1:255
	v_and_or_b32 v21, v21, s90, v19
	s_waitcnt lgkmcnt(3)
	v_bfe_u32 v19, v32, 16, 1
	v_add3_u32 v19, v32, v19, s87
	s_waitcnt lgkmcnt(2)
	v_bfe_u32 v22, v34, 16, 1
	v_lshrrev_b32_e32 v19, 16, v19
	v_add3_u32 v22, v34, v22, s87
	v_and_or_b32 v22, v22, s90, v19
	s_waitcnt lgkmcnt(1)
	v_bfe_u32 v19, v36, 16, 1
	v_add3_u32 v19, v36, v19, s87
	s_waitcnt lgkmcnt(0)
	v_bfe_u32 v23, v38, 16, 1
	v_lshrrev_b32_e32 v19, 16, v19
	v_add3_u32 v23, v38, v23, s87
	v_and_or_b32 v23, v23, s90, v19
	v_or_b32_e32 v19, s4, v16
	v_lshlrev_b32_e32 v40, 7, v19
	v_mov_b32_e32 v41, v2
	v_lshl_add_u64 v[40:41], v[8:9], 0, v[40:41]
	v_bfe_u32 v19, v27, 16, 1
	global_store_dwordx4 v[40:41], v[20:23], off nt
	v_add3_u32 v19, v27, v19, s87
	v_lshrrev_b32_e32 v19, 16, v19
	v_bfe_u32 v20, v25, 16, 1
	v_add3_u32 v20, v25, v20, s87
	v_and_or_b32 v20, v20, s90, v19
	v_bfe_u32 v19, v29, 16, 1
	v_add3_u32 v19, v29, v19, s87
	v_bfe_u32 v21, v31, 16, 1
	v_lshrrev_b32_e32 v19, 16, v19
	v_add3_u32 v21, v31, v21, s87
	v_and_or_b32 v21, v21, s90, v19
	v_bfe_u32 v19, v33, 16, 1
	v_add3_u32 v19, v33, v19, s87
	v_bfe_u32 v22, v35, 16, 1
	v_lshrrev_b32_e32 v19, 16, v19
	v_add3_u32 v22, v35, v22, s87
	v_and_or_b32 v22, v22, s90, v19
	v_bfe_u32 v19, v37, 16, 1
	v_add3_u32 v19, v37, v19, s87
	v_bfe_u32 v23, v39, 16, 1
	v_lshrrev_b32_e32 v19, 16, v19
	v_add3_u32 v23, v39, v23, s87
	v_and_or_b32 v23, v23, s90, v19
	v_or_b32_e32 v19, s4, v17
	v_lshlrev_b32_e32 v24, 7, v19
	v_mov_b32_e32 v25, v2
	v_lshl_add_u64 v[8:9], v[8:9], 0, v[24:25]
	global_store_dwordx4 v[8:9], v[20:23], off nt
	s_waitcnt lgkmcnt(0)
	s_mov_b64 s[4:5], 0

.Lcv_nopf_b:
	s_cmp_lg_u32 s86, 0
	ds_write2_b32 v5, v20, v21 offset1:1
	ds_write2_b32 v5, v22, v23 offset0:2 offset1:3
	ds_write2_b32 v8, v24, v25 offset1:1
	v_add_u32_e32 v8, 0x418, v5
	ds_write2_b32 v8, v26, v27 offset1:1
	v_add_u32_e32 v8, 0x820, v5
	s_add_i32 s5, s48, s51
	s_ashr_i32 s4, s4, 8
	s_add_i32 s8, s5, 0xfffc0000
	ds_write2_b32 v8, v28, v29 offset1:1
	v_add_u32_e32 v8, 0x828, v5
	ds_write2_b32 v8, v30, v31 offset1:1
	v_add_u32_e32 v8, 0xc30, v5
	ds_write2_b32 v8, v32, v33 offset1:1
	v_add_u32_e32 v8, 0xc38, v5
	ds_write2_b32 v8, v34, v35 offset1:1
	v_add_u32_e32 v8, 0x1040, v5
	s_ashr_i32 s5, s4, 31
	s_lshl_b64 s[4:5], s[4:5], 21
	s_lshl_b32 s9, s16, 15
	ds_write2_b32 v8, v36, v37 offset1:1
	v_add_u32_e32 v8, 0x1048, v5
	ds_write2_b32 v8, v38, v39 offset1:1
	v_add_u32_e32 v8, 0x1450, v5
	ds_write2_b32 v8, v40, v41 offset1:1
	v_add_u32_e32 v8, 0x1458, v5
	ds_write2_b32 v8, v42, v43 offset1:1
	v_add_u32_e32 v8, 0x1860, v5
	v_add_u32_e32 v42, 0x400, v10
	s_waitcnt lgkmcnt(0)
	s_add_u32 s4, s6, s4
	s_addc_u32 s5, s7, s5
	ds_write2_b32 v8, v44, v45 offset1:1
	v_add_u32_e32 v8, 0x1868, v5
	ds_write2_b32 v8, v46, v47 offset1:1
	v_add_u32_e32 v8, 0x1c70, v5
	ds_write2_b32 v8, v48, v49 offset1:1
	v_add_u32_e32 v8, 0x1c78, v5
	ds_write2_b32 v8, v50, v51 offset1:1
	v_add_u32_e32 v8, 0x2080, v5
	s_add_u32 s6, s4, s9
	s_addc_u32 s7, s5, 0
	s_and_b32 s4, s8, 0xc0
	ds_write2_b32 v8, v52, v53 offset1:1
	v_add_u32_e32 v8, 0x2088, v5
	ds_write2_b32 v8, v54, v55 offset1:1
	v_add_u32_e32 v8, 0x2490, v5
	ds_write2_b32 v8, v56, v57 offset1:1
	v_add_u32_e32 v8, 0x2498, v5
	ds_write2_b32 v8, v58, v59 offset1:1
	v_add_u32_e32 v8, 0x28a0, v5
	v_mov_b32_e32 v9, v2
	v_mov_b32_e32 v41, v2
	ds_write2_b32 v8, v60, v61 offset1:1
	v_add_u32_e32 v8, 0x28a8, v5
	ds_write2_b32 v8, v62, v63 offset1:1
	v_add_u32_e32 v8, 0x2cb0, v5
	ds_write2_b32 v8, v64, v65 offset1:1
	v_add_u32_e32 v8, 0x2cb8, v5
	ds_write2_b32 v8, v66, v67 offset1:1
	v_add_u32_e32 v8, 0x30c0, v5
	ds_write2_b32 v8, v68, v69 offset1:1
	v_add_u32_e32 v8, 0x30c8, v5
	ds_write2_b32 v8, v70, v71 offset1:1
	v_add_u32_e32 v8, 0x34d0, v5
	ds_write2_b32 v8, v72, v73 offset1:1
	v_add_u32_e32 v8, 0x34d8, v5
	ds_write2_b32 v8, v74, v75 offset1:1
	v_add_u32_e32 v8, 0x38e0, v5
	ds_write2_b32 v8, v76, v77 offset1:1
	v_add_u32_e32 v8, 0x38e8, v5
	ds_write2_b32 v8, v78, v79 offset1:1
	v_add_u32_e32 v8, 0x3cf0, v5
	ds_write2_b32 v8, v80, v81 offset1:1
	v_add_u32_e32 v8, 0x3cf8, v5
	ds_write2_b32 v8, v82, v83 offset1:1
	s_waitcnt lgkmcnt(0)
	ds_read2_b32 v[24:25], v10 offset1:8
	ds_read2_b32 v[26:27], v10 offset0:65 offset1:73
	ds_read2_b32 v[28:29], v10 offset0:130 offset1:138
	ds_read2_b32 v[30:31], v10 offset0:195 offset1:203
	ds_read2_b32 v[32:33], v42 offset0:4 offset1:12
	s_waitcnt lgkmcnt(4)
	v_bfe_u32 v19, v24, 16, 1
	v_add3_u32 v19, v24, v19, s87
	s_waitcnt lgkmcnt(3)
	v_bfe_u32 v20, v26, 16, 1
	v_lshrrev_b32_e32 v19, 16, v19
	v_add3_u32 v20, v26, v20, s87
	ds_read2_b32 v[34:35], v42 offset0:69 offset1:77
	v_and_or_b32 v20, v20, s90, v19
	s_waitcnt lgkmcnt(3)
	v_bfe_u32 v19, v28, 16, 1
	v_add3_u32 v19, v28, v19, s87
	s_waitcnt lgkmcnt(2)
	v_bfe_u32 v21, v30, 16, 1
	ds_read2_b32 v[36:37], v42 offset0:134 offset1:142
	v_lshrrev_b32_e32 v19, 16, v19
	v_add3_u32 v21, v30, v21, s87
	ds_read2_b32 v[38:39], v42 offset0:199 offset1:207
	v_and_or_b32 v21, v21, s90, v19
	s_waitcnt lgkmcnt(3)
	v_bfe_u32 v19, v32, 16, 1
	v_add3_u32 v19, v32, v19, s87
	s_waitcnt lgkmcnt(2)
	v_bfe_u32 v22, v34, 16, 1
	v_lshrrev_b32_e32 v19, 16, v19
	v_add3_u32 v22, v34, v22, s87
	v_and_or_b32 v22, v22, s90, v19
	s_waitcnt lgkmcnt(1)
	v_bfe_u32 v19, v36, 16, 1
	v_add3_u32 v19, v36, v19, s87
	s_waitcnt lgkmcnt(0)
	v_bfe_u32 v23, v38, 16, 1
	v_lshlrev_b32_e32 v8, 1, v6
	v_lshrrev_b32_e32 v19, 16, v19
	v_add3_u32 v23, v38, v23, s87
	v_lshl_add_u64 v[8:9], s[6:7], 0, v[8:9]
	s_mov_b64 s[6:7], 0x8400000
	v_and_or_b32 v23, v23, s90, v19
	v_or_b32_e32 v19, s4, v7
	v_lshl_add_u64 v[8:9], v[8:9], 0, s[6:7]
	v_lshlrev_b32_e32 v40, 7, v19
	v_lshl_add_u64 v[40:41], v[8:9], 0, v[40:41]
	v_bfe_u32 v19, v25, 16, 1
	global_store_dwordx4 v[40:41], v[20:23], off nt
	v_add3_u32 v19, v25, v19, s87
	v_lshrrev_b32_e32 v19, 16, v19
	v_bfe_u32 v20, v27, 16, 1
	v_add3_u32 v20, v27, v20, s87
	v_and_or_b32 v20, v20, s90, v19
	v_bfe_u32 v19, v29, 16, 1
	v_add3_u32 v19, v29, v19, s87
	v_bfe_u32 v21, v31, 16, 1
	v_lshrrev_b32_e32 v19, 16, v19
	v_add3_u32 v21, v31, v21, s87
	v_and_or_b32 v21, v21, s90, v19
	v_bfe_u32 v19, v33, 16, 1
	v_add3_u32 v19, v33, v19, s87
	v_bfe_u32 v22, v35, 16, 1
	v_lshrrev_b32_e32 v19, 16, v19
	v_add3_u32 v22, v35, v22, s87
	v_and_or_b32 v22, v22, s90, v19
	v_bfe_u32 v19, v37, 16, 1
	v_add3_u32 v19, v37, v19, s87
	v_bfe_u32 v23, v39, 16, 1
	v_lshrrev_b32_e32 v19, 16, v19
	v_add3_u32 v23, v39, v23, s87
	v_and_or_b32 v23, v23, s90, v19
	v_or_b32_e32 v19, s4, v11
	v_lshlrev_b32_e32 v24, 7, v19
	v_mov_b32_e32 v25, v2
	ds_read2_b32 v[26:27], v10 offset0:16 offset1:24
	v_lshl_add_u64 v[24:25], v[8:9], 0, v[24:25]
	global_store_dwordx4 v[24:25], v[20:23], off nt
	ds_read2_b32 v[24:25], v10 offset0:81 offset1:89
	ds_read2_b32 v[28:29], v10 offset0:146 offset1:154
	ds_read2_b32 v[30:31], v10 offset0:211 offset1:219
	s_waitcnt lgkmcnt(3)
	v_bfe_u32 v19, v26, 16, 1
	v_add3_u32 v19, v26, v19, s87
	s_waitcnt lgkmcnt(2)
	v_bfe_u32 v20, v24, 16, 1
	ds_read2_b32 v[32:33], v42 offset0:20 offset1:28
	v_lshrrev_b32_e32 v19, 16, v19
	v_add3_u32 v20, v24, v20, s87
	ds_read2_b32 v[34:35], v42 offset0:85 offset1:93
	v_and_or_b32 v20, v20, s90, v19
	s_waitcnt lgkmcnt(3)
	v_bfe_u32 v19, v28, 16, 1
	v_add3_u32 v19, v28, v19, s87
	s_waitcnt lgkmcnt(2)
	v_bfe_u32 v21, v30, 16, 1
	ds_read2_b32 v[36:37], v42 offset0:150 offset1:158
	v_lshrrev_b32_e32 v19, 16, v19
	v_add3_u32 v21, v30, v21, s87
	ds_read2_b32 v[38:39], v42 offset0:215 offset1:223
	v_and_or_b32 v21, v21, s90, v19
	s_waitcnt lgkmcnt(3)
	v_bfe_u32 v19, v32, 16, 1
	v_add3_u32 v19, v32, v19, s87
	s_waitcnt lgkmcnt(2)
	v_bfe_u32 v22, v34, 16, 1
	v_lshrrev_b32_e32 v19, 16, v19
	v_add3_u32 v22, v34, v22, s87
	v_and_or_b32 v22, v22, s90, v19
	s_waitcnt lgkmcnt(1)
	v_bfe_u32 v19, v36, 16, 1
	v_add3_u32 v19, v36, v19, s87
	s_waitcnt lgkmcnt(0)
	v_bfe_u32 v23, v38, 16, 1
	v_lshrrev_b32_e32 v19, 16, v19
	v_add3_u32 v23, v38, v23, s87
	v_and_or_b32 v23, v23, s90, v19
	v_or_b32_e32 v19, s4, v12
	v_lshlrev_b32_e32 v40, 7, v19
	v_mov_b32_e32 v41, v2
	v_lshl_add_u64 v[40:41], v[8:9], 0, v[40:41]
	v_bfe_u32 v19, v27, 16, 1
	global_store_dwordx4 v[40:41], v[20:23], off nt
	v_add3_u32 v19, v27, v19, s87
	v_lshrrev_b32_e32 v19, 16, v19
	v_bfe_u32 v20, v25, 16, 1
	v_add3_u32 v20, v25, v20, s87
	v_and_or_b32 v20, v20, s90, v19
	v_bfe_u32 v19, v29, 16, 1
	v_add3_u32 v19, v29, v19, s87
	v_bfe_u32 v21, v31, 16, 1
	v_lshrrev_b32_e32 v19, 16, v19
	v_add3_u32 v21, v31, v21, s87
	v_and_or_b32 v21, v21, s90, v19
	v_bfe_u32 v19, v33, 16, 1
	v_add3_u32 v19, v33, v19, s87
	v_bfe_u32 v22, v35, 16, 1
	v_lshrrev_b32_e32 v19, 16, v19
	v_add3_u32 v22, v35, v22, s87
	v_and_or_b32 v22, v22, s90, v19
	v_bfe_u32 v19, v37, 16, 1
	v_add3_u32 v19, v37, v19, s87
	v_bfe_u32 v23, v39, 16, 1
	v_lshrrev_b32_e32 v19, 16, v19
	v_add3_u32 v23, v39, v23, s87
	v_and_or_b32 v23, v23, s90, v19
	v_or_b32_e32 v19, s4, v13
	v_lshlrev_b32_e32 v24, 7, v19
	v_mov_b32_e32 v25, v2
	ds_read2_b32 v[26:27], v10 offset0:32 offset1:40
	v_lshl_add_u64 v[24:25], v[8:9], 0, v[24:25]
	global_store_dwordx4 v[24:25], v[20:23], off nt
	ds_read2_b32 v[24:25], v10 offset0:97 offset1:105
	ds_read2_b32 v[28:29], v10 offset0:162 offset1:170
	ds_read2_b32 v[30:31], v10 offset0:227 offset1:235
	s_waitcnt lgkmcnt(3)
	v_bfe_u32 v19, v26, 16, 1
	v_add3_u32 v19, v26, v19, s87
	s_waitcnt lgkmcnt(2)
	v_bfe_u32 v20, v24, 16, 1
	ds_read2_b32 v[32:33], v42 offset0:36 offset1:44
	v_lshrrev_b32_e32 v19, 16, v19
	v_add3_u32 v20, v24, v20, s87
	ds_read2_b32 v[34:35], v42 offset0:101 offset1:109
	v_and_or_b32 v20, v20, s90, v19
	s_waitcnt lgkmcnt(3)
	v_bfe_u32 v19, v28, 16, 1
	v_add3_u32 v19, v28, v19, s87
	s_waitcnt lgkmcnt(2)
	v_bfe_u32 v21, v30, 16, 1
	ds_read2_b32 v[36:37], v42 offset0:166 offset1:174
	v_lshrrev_b32_e32 v19, 16, v19
	v_add3_u32 v21, v30, v21, s87
	ds_read2_b32 v[38:39], v42 offset0:231 offset1:239
	v_and_or_b32 v21, v21, s90, v19
	s_waitcnt lgkmcnt(3)
	v_bfe_u32 v19, v32, 16, 1
	v_add3_u32 v19, v32, v19, s87
	s_waitcnt lgkmcnt(2)
	v_bfe_u32 v22, v34, 16, 1
	v_lshrrev_b32_e32 v19, 16, v19
	v_add3_u32 v22, v34, v22, s87
	v_and_or_b32 v22, v22, s90, v19
	s_waitcnt lgkmcnt(1)
	v_bfe_u32 v19, v36, 16, 1
	v_add3_u32 v19, v36, v19, s87
	s_waitcnt lgkmcnt(0)
	v_bfe_u32 v23, v38, 16, 1
	v_lshrrev_b32_e32 v19, 16, v19
	v_add3_u32 v23, v38, v23, s87
	v_and_or_b32 v23, v23, s90, v19
	v_or_b32_e32 v19, s4, v14
	v_lshlrev_b32_e32 v40, 7, v19
	v_mov_b32_e32 v41, v2
	v_lshl_add_u64 v[40:41], v[8:9], 0, v[40:41]
	v_bfe_u32 v19, v27, 16, 1
	global_store_dwordx4 v[40:41], v[20:23], off nt
	v_add3_u32 v19, v27, v19, s87
	v_lshrrev_b32_e32 v19, 16, v19
	v_bfe_u32 v20, v25, 16, 1
	v_add3_u32 v20, v25, v20, s87
	v_and_or_b32 v20, v20, s90, v19
	v_bfe_u32 v19, v29, 16, 1
	v_add3_u32 v19, v29, v19, s87
	v_bfe_u32 v21, v31, 16, 1
	v_lshrrev_b32_e32 v19, 16, v19
	v_add3_u32 v21, v31, v21, s87
	v_and_or_b32 v21, v21, s90, v19
	v_bfe_u32 v19, v33, 16, 1
	v_add3_u32 v19, v33, v19, s87
	v_bfe_u32 v22, v35, 16, 1
	v_lshrrev_b32_e32 v19, 16, v19
	v_add3_u32 v22, v35, v22, s87
	v_and_or_b32 v22, v22, s90, v19
	v_bfe_u32 v19, v37, 16, 1
	v_add3_u32 v19, v37, v19, s87
	v_bfe_u32 v23, v39, 16, 1
	v_lshrrev_b32_e32 v19, 16, v19
	v_add3_u32 v23, v39, v23, s87
	v_and_or_b32 v23, v23, s90, v19
	v_or_b32_e32 v19, s4, v15
	v_lshlrev_b32_e32 v24, 7, v19
	v_mov_b32_e32 v25, v2
	ds_read2_b32 v[26:27], v10 offset0:48 offset1:56
	v_lshl_add_u64 v[24:25], v[8:9], 0, v[24:25]
	global_store_dwordx4 v[24:25], v[20:23], off nt
	ds_read2_b32 v[24:25], v10 offset0:113 offset1:121
	ds_read2_b32 v[28:29], v10 offset0:178 offset1:186
	ds_read2_b32 v[30:31], v10 offset0:243 offset1:251
	s_waitcnt lgkmcnt(3)
	v_bfe_u32 v19, v26, 16, 1
	v_add3_u32 v19, v26, v19, s87
	s_waitcnt lgkmcnt(2)
	v_bfe_u32 v20, v24, 16, 1
	ds_read2_b32 v[32:33], v42 offset0:52 offset1:60
	v_lshrrev_b32_e32 v19, 16, v19
	v_add3_u32 v20, v24, v20, s87
	ds_read2_b32 v[34:35], v42 offset0:117 offset1:125
	v_and_or_b32 v20, v20, s90, v19
	s_waitcnt lgkmcnt(3)
	v_bfe_u32 v19, v28, 16, 1
	v_add3_u32 v19, v28, v19, s87
	s_waitcnt lgkmcnt(2)
	v_bfe_u32 v21, v30, 16, 1
	ds_read2_b32 v[36:37], v42 offset0:182 offset1:190
	v_lshrrev_b32_e32 v19, 16, v19
	v_add3_u32 v21, v30, v21, s87
	ds_read2_b32 v[38:39], v42 offset0:247 offset1:255
	v_and_or_b32 v21, v21, s90, v19
	s_waitcnt lgkmcnt(3)
	v_bfe_u32 v19, v32, 16, 1
	v_add3_u32 v19, v32, v19, s87
	s_waitcnt lgkmcnt(2)
	v_bfe_u32 v22, v34, 16, 1
	v_lshrrev_b32_e32 v19, 16, v19
	v_add3_u32 v22, v34, v22, s87
	v_and_or_b32 v22, v22, s90, v19
	s_waitcnt lgkmcnt(1)
	v_bfe_u32 v19, v36, 16, 1
	v_add3_u32 v19, v36, v19, s87
	s_waitcnt lgkmcnt(0)
	v_bfe_u32 v23, v38, 16, 1
	v_lshrrev_b32_e32 v19, 16, v19
	v_add3_u32 v23, v38, v23, s87
	v_and_or_b32 v23, v23, s90, v19
	v_or_b32_e32 v19, s4, v16
	v_lshlrev_b32_e32 v40, 7, v19
	v_mov_b32_e32 v41, v2
	v_lshl_add_u64 v[40:41], v[8:9], 0, v[40:41]
	v_bfe_u32 v19, v27, 16, 1
	global_store_dwordx4 v[40:41], v[20:23], off nt
	v_add3_u32 v19, v27, v19, s87
	v_lshrrev_b32_e32 v19, 16, v19
	v_bfe_u32 v20, v25, 16, 1
	v_add3_u32 v20, v25, v20, s87
	v_and_or_b32 v20, v20, s90, v19
	v_bfe_u32 v19, v29, 16, 1
	v_add3_u32 v19, v29, v19, s87
	v_bfe_u32 v21, v31, 16, 1
	v_lshrrev_b32_e32 v19, 16, v19
	v_add3_u32 v21, v31, v21, s87
	v_and_or_b32 v21, v21, s90, v19
	v_bfe_u32 v19, v33, 16, 1
	v_add3_u32 v19, v33, v19, s87
	v_bfe_u32 v22, v35, 16, 1
	v_lshrrev_b32_e32 v19, 16, v19
	v_add3_u32 v22, v35, v22, s87
	v_and_or_b32 v22, v22, s90, v19
	v_bfe_u32 v19, v37, 16, 1
	v_add3_u32 v19, v37, v19, s87
	v_bfe_u32 v23, v39, 16, 1
	v_lshrrev_b32_e32 v19, 16, v19
	v_add3_u32 v23, v39, v23, s87
	v_and_or_b32 v23, v23, s90, v19
	v_or_b32_e32 v19, s4, v17
	v_lshlrev_b32_e32 v24, 7, v19
	v_mov_b32_e32 v25, v2
	v_lshl_add_u64 v[8:9], v[8:9], 0, v[24:25]
	global_store_dwordx4 v[8:9], v[20:23], off nt
	s_waitcnt lgkmcnt(0)

.Lcv_nopf_c:
	s_cmp_lg_u32 s86, 0
	ds_write2_b32 v5, v20, v21 offset1:1
	ds_write2_b32 v5, v22, v23 offset0:2 offset1:3
	ds_write2_b32 v8, v24, v25 offset1:1
	v_add_u32_e32 v8, 0x418, v5
	ds_write2_b32 v8, v26, v27 offset1:1
	v_add_u32_e32 v8, 0x820, v5
	s_addc_u32 s7, s7, s5
	s_and_b32 s4, s12, 0xc0
	v_mov_b32_e32 v9, v2
	ds_write2_b32 v8, v28, v29 offset1:1
	v_add_u32_e32 v8, 0x828, v5
	ds_write2_b32 v8, v30, v31 offset1:1
	v_add_u32_e32 v8, 0xc30, v5
	ds_write2_b32 v8, v32, v33 offset1:1
	v_add_u32_e32 v8, 0xc38, v5
	ds_write2_b32 v8, v34, v35 offset1:1
	v_add_u32_e32 v8, 0x1040, v5
	ds_write2_b32 v8, v36, v37 offset1:1
	v_add_u32_e32 v8, 0x1048, v5
	ds_write2_b32 v8, v38, v39 offset1:1
	v_add_u32_e32 v8, 0x1450, v5
	ds_write2_b32 v8, v40, v41 offset1:1
	v_add_u32_e32 v8, 0x1458, v5
	ds_write2_b32 v8, v42, v43 offset1:1
	v_add_u32_e32 v8, 0x1860, v5
	v_add_u32_e32 v42, 0x400, v10
	v_mov_b32_e32 v41, v2
	ds_write2_b32 v8, v44, v45 offset1:1
	v_add_u32_e32 v8, 0x1868, v5
	ds_write2_b32 v8, v46, v47 offset1:1
	v_add_u32_e32 v8, 0x1c70, v5
	ds_write2_b32 v8, v48, v49 offset1:1
	v_add_u32_e32 v8, 0x1c78, v5
	ds_write2_b32 v8, v50, v51 offset1:1
	v_add_u32_e32 v8, 0x2080, v5
	ds_write2_b32 v8, v52, v53 offset1:1
	v_add_u32_e32 v8, 0x2088, v5
	ds_write2_b32 v8, v54, v55 offset1:1
	v_add_u32_e32 v8, 0x2490, v5
	ds_write2_b32 v8, v56, v57 offset1:1
	v_add_u32_e32 v8, 0x2498, v5
	ds_write2_b32 v8, v58, v59 offset1:1
	v_add_u32_e32 v8, 0x28a0, v5
	ds_write2_b32 v8, v60, v61 offset1:1
	v_add_u32_e32 v8, 0x28a8, v5
	ds_write2_b32 v8, v62, v63 offset1:1
	v_add_u32_e32 v8, 0x2cb0, v5
	ds_write2_b32 v8, v64, v65 offset1:1
	v_add_u32_e32 v8, 0x2cb8, v5
	ds_write2_b32 v8, v66, v67 offset1:1
	v_add_u32_e32 v8, 0x30c0, v5
	ds_write2_b32 v8, v68, v69 offset1:1
	v_add_u32_e32 v8, 0x30c8, v5
	ds_write2_b32 v8, v70, v71 offset1:1
	v_add_u32_e32 v8, 0x34d0, v5
	ds_write2_b32 v8, v72, v73 offset1:1
	v_add_u32_e32 v8, 0x34d8, v5
	ds_write2_b32 v8, v74, v75 offset1:1
	v_add_u32_e32 v8, 0x38e0, v5
	ds_write2_b32 v8, v76, v77 offset1:1
	v_add_u32_e32 v8, 0x38e8, v5
	ds_write2_b32 v8, v78, v79 offset1:1
	v_add_u32_e32 v8, 0x3cf0, v5
	ds_write2_b32 v8, v80, v81 offset1:1
	v_add_u32_e32 v8, 0x3cf8, v5
	ds_write2_b32 v8, v82, v83 offset1:1
	s_waitcnt lgkmcnt(0)
	ds_read2_b32 v[24:25], v10 offset1:8
	ds_read2_b32 v[26:27], v10 offset0:65 offset1:73
	ds_read2_b32 v[28:29], v10 offset0:130 offset1:138
	ds_read2_b32 v[30:31], v10 offset0:195 offset1:203
	ds_read2_b32 v[32:33], v42 offset0:4 offset1:12
	s_waitcnt lgkmcnt(4)
	v_bfe_u32 v19, v24, 16, 1
	v_add3_u32 v19, v24, v19, s87
	s_waitcnt lgkmcnt(3)
	v_bfe_u32 v20, v26, 16, 1
	v_lshrrev_b32_e32 v19, 16, v19
	v_add3_u32 v20, v26, v20, s87
	ds_read2_b32 v[34:35], v42 offset0:69 offset1:77
	v_and_or_b32 v20, v20, s90, v19
	s_waitcnt lgkmcnt(3)
	v_bfe_u32 v19, v28, 16, 1
	v_add3_u32 v19, v28, v19, s87
	s_waitcnt lgkmcnt(2)
	v_bfe_u32 v21, v30, 16, 1
	ds_read2_b32 v[36:37], v42 offset0:134 offset1:142
	v_lshrrev_b32_e32 v19, 16, v19
	v_add3_u32 v21, v30, v21, s87
	ds_read2_b32 v[38:39], v42 offset0:199 offset1:207
	v_and_or_b32 v21, v21, s90, v19
	s_waitcnt lgkmcnt(3)
	v_bfe_u32 v19, v32, 16, 1
	v_add3_u32 v19, v32, v19, s87
	s_waitcnt lgkmcnt(2)
	v_bfe_u32 v22, v34, 16, 1
	v_lshrrev_b32_e32 v19, 16, v19
	v_add3_u32 v22, v34, v22, s87
	v_and_or_b32 v22, v22, s90, v19
	s_waitcnt lgkmcnt(1)
	v_bfe_u32 v19, v36, 16, 1
	v_add3_u32 v19, v36, v19, s87
	s_waitcnt lgkmcnt(0)
	v_bfe_u32 v23, v38, 16, 1
	v_lshlrev_b32_e32 v8, 1, v6
	v_lshrrev_b32_e32 v19, 16, v19
	v_add3_u32 v23, v38, v23, s87
	v_lshl_add_u64 v[8:9], s[6:7], 0, v[8:9]
	s_mov_b64 s[6:7], 0x6400000
	v_and_or_b32 v23, v23, s90, v19
	v_or_b32_e32 v19, s4, v7
	v_lshl_add_u64 v[8:9], v[8:9], 0, s[6:7]
	v_lshlrev_b32_e32 v40, 7, v19
	v_lshl_add_u64 v[40:41], v[8:9], 0, v[40:41]
	v_bfe_u32 v19, v25, 16, 1
	global_store_dwordx4 v[40:41], v[20:23], off nt
	v_add3_u32 v19, v25, v19, s87
	v_lshrrev_b32_e32 v19, 16, v19
	v_bfe_u32 v20, v27, 16, 1
	v_add3_u32 v20, v27, v20, s87
	v_and_or_b32 v20, v20, s90, v19
	v_bfe_u32 v19, v29, 16, 1
	v_add3_u32 v19, v29, v19, s87
	v_bfe_u32 v21, v31, 16, 1
	v_lshrrev_b32_e32 v19, 16, v19
	v_add3_u32 v21, v31, v21, s87
	v_and_or_b32 v21, v21, s90, v19
	v_bfe_u32 v19, v33, 16, 1
	v_add3_u32 v19, v33, v19, s87
	v_bfe_u32 v22, v35, 16, 1
	v_lshrrev_b32_e32 v19, 16, v19
	v_add3_u32 v22, v35, v22, s87
	v_and_or_b32 v22, v22, s90, v19
	v_bfe_u32 v19, v37, 16, 1
	v_add3_u32 v19, v37, v19, s87
	v_bfe_u32 v23, v39, 16, 1
	v_lshrrev_b32_e32 v19, 16, v19
	v_add3_u32 v23, v39, v23, s87
	v_and_or_b32 v23, v23, s90, v19
	v_or_b32_e32 v19, s4, v11
	v_lshlrev_b32_e32 v24, 7, v19
	v_mov_b32_e32 v25, v2
	ds_read2_b32 v[26:27], v10 offset0:16 offset1:24
	v_lshl_add_u64 v[24:25], v[8:9], 0, v[24:25]
	global_store_dwordx4 v[24:25], v[20:23], off nt
	ds_read2_b32 v[24:25], v10 offset0:81 offset1:89
	ds_read2_b32 v[28:29], v10 offset0:146 offset1:154
	ds_read2_b32 v[30:31], v10 offset0:211 offset1:219
	s_waitcnt lgkmcnt(3)
	v_bfe_u32 v19, v26, 16, 1
	v_add3_u32 v19, v26, v19, s87
	s_waitcnt lgkmcnt(2)
	v_bfe_u32 v20, v24, 16, 1
	ds_read2_b32 v[32:33], v42 offset0:20 offset1:28
	v_lshrrev_b32_e32 v19, 16, v19
	v_add3_u32 v20, v24, v20, s87
	ds_read2_b32 v[34:35], v42 offset0:85 offset1:93
	v_and_or_b32 v20, v20, s90, v19
	s_waitcnt lgkmcnt(3)
	v_bfe_u32 v19, v28, 16, 1
	v_add3_u32 v19, v28, v19, s87
	s_waitcnt lgkmcnt(2)
	v_bfe_u32 v21, v30, 16, 1
	ds_read2_b32 v[36:37], v42 offset0:150 offset1:158
	v_lshrrev_b32_e32 v19, 16, v19
	v_add3_u32 v21, v30, v21, s87
	ds_read2_b32 v[38:39], v42 offset0:215 offset1:223
	v_and_or_b32 v21, v21, s90, v19
	s_waitcnt lgkmcnt(3)
	v_bfe_u32 v19, v32, 16, 1
	v_add3_u32 v19, v32, v19, s87
	s_waitcnt lgkmcnt(2)
	v_bfe_u32 v22, v34, 16, 1
	v_lshrrev_b32_e32 v19, 16, v19
	v_add3_u32 v22, v34, v22, s87
	v_and_or_b32 v22, v22, s90, v19
	s_waitcnt lgkmcnt(1)
	v_bfe_u32 v19, v36, 16, 1
	v_add3_u32 v19, v36, v19, s87
	s_waitcnt lgkmcnt(0)
	v_bfe_u32 v23, v38, 16, 1
	v_lshrrev_b32_e32 v19, 16, v19
	v_add3_u32 v23, v38, v23, s87
	v_and_or_b32 v23, v23, s90, v19
	v_or_b32_e32 v19, s4, v12
	v_lshlrev_b32_e32 v40, 7, v19
	v_mov_b32_e32 v41, v2
	v_lshl_add_u64 v[40:41], v[8:9], 0, v[40:41]
	v_bfe_u32 v19, v27, 16, 1
	global_store_dwordx4 v[40:41], v[20:23], off nt
	v_add3_u32 v19, v27, v19, s87
	v_lshrrev_b32_e32 v19, 16, v19
	v_bfe_u32 v20, v25, 16, 1
	v_add3_u32 v20, v25, v20, s87
	v_and_or_b32 v20, v20, s90, v19
	v_bfe_u32 v19, v29, 16, 1
	v_add3_u32 v19, v29, v19, s87
	v_bfe_u32 v21, v31, 16, 1
	v_lshrrev_b32_e32 v19, 16, v19
	v_add3_u32 v21, v31, v21, s87
	v_and_or_b32 v21, v21, s90, v19
	v_bfe_u32 v19, v33, 16, 1
	v_add3_u32 v19, v33, v19, s87
	v_bfe_u32 v22, v35, 16, 1
	v_lshrrev_b32_e32 v19, 16, v19
	v_add3_u32 v22, v35, v22, s87
	v_and_or_b32 v22, v22, s90, v19
	v_bfe_u32 v19, v37, 16, 1
	v_add3_u32 v19, v37, v19, s87
	v_bfe_u32 v23, v39, 16, 1
	v_lshrrev_b32_e32 v19, 16, v19
	v_add3_u32 v23, v39, v23, s87
	v_and_or_b32 v23, v23, s90, v19
	v_or_b32_e32 v19, s4, v13
	v_lshlrev_b32_e32 v24, 7, v19
	v_mov_b32_e32 v25, v2
	ds_read2_b32 v[26:27], v10 offset0:32 offset1:40
	v_lshl_add_u64 v[24:25], v[8:9], 0, v[24:25]
	global_store_dwordx4 v[24:25], v[20:23], off nt
	ds_read2_b32 v[24:25], v10 offset0:97 offset1:105
	ds_read2_b32 v[28:29], v10 offset0:162 offset1:170
	ds_read2_b32 v[30:31], v10 offset0:227 offset1:235
	s_waitcnt lgkmcnt(3)
	v_bfe_u32 v19, v26, 16, 1
	v_add3_u32 v19, v26, v19, s87
	s_waitcnt lgkmcnt(2)
	v_bfe_u32 v20, v24, 16, 1
	ds_read2_b32 v[32:33], v42 offset0:36 offset1:44
	v_lshrrev_b32_e32 v19, 16, v19
	v_add3_u32 v20, v24, v20, s87
	ds_read2_b32 v[34:35], v42 offset0:101 offset1:109
	v_and_or_b32 v20, v20, s90, v19
	s_waitcnt lgkmcnt(3)
	v_bfe_u32 v19, v28, 16, 1
	v_add3_u32 v19, v28, v19, s87
	s_waitcnt lgkmcnt(2)
	v_bfe_u32 v21, v30, 16, 1
	ds_read2_b32 v[36:37], v42 offset0:166 offset1:174
	v_lshrrev_b32_e32 v19, 16, v19
	v_add3_u32 v21, v30, v21, s87
	ds_read2_b32 v[38:39], v42 offset0:231 offset1:239
	v_and_or_b32 v21, v21, s90, v19
	s_waitcnt lgkmcnt(3)
	v_bfe_u32 v19, v32, 16, 1
	v_add3_u32 v19, v32, v19, s87
	s_waitcnt lgkmcnt(2)
	v_bfe_u32 v22, v34, 16, 1
	v_lshrrev_b32_e32 v19, 16, v19
	v_add3_u32 v22, v34, v22, s87
	v_and_or_b32 v22, v22, s90, v19
	s_waitcnt lgkmcnt(1)
	v_bfe_u32 v19, v36, 16, 1
	v_add3_u32 v19, v36, v19, s87
	s_waitcnt lgkmcnt(0)
	v_bfe_u32 v23, v38, 16, 1
	v_lshrrev_b32_e32 v19, 16, v19
	v_add3_u32 v23, v38, v23, s87
	v_and_or_b32 v23, v23, s90, v19
	v_or_b32_e32 v19, s4, v14
	v_lshlrev_b32_e32 v40, 7, v19
	v_mov_b32_e32 v41, v2
	v_lshl_add_u64 v[40:41], v[8:9], 0, v[40:41]
	v_bfe_u32 v19, v27, 16, 1
	global_store_dwordx4 v[40:41], v[20:23], off nt
	v_add3_u32 v19, v27, v19, s87
	v_lshrrev_b32_e32 v19, 16, v19
	v_bfe_u32 v20, v25, 16, 1
	v_add3_u32 v20, v25, v20, s87
	v_and_or_b32 v20, v20, s90, v19
	v_bfe_u32 v19, v29, 16, 1
	v_add3_u32 v19, v29, v19, s87
	v_bfe_u32 v21, v31, 16, 1
	v_lshrrev_b32_e32 v19, 16, v19
	v_add3_u32 v21, v31, v21, s87
	v_and_or_b32 v21, v21, s90, v19
	v_bfe_u32 v19, v33, 16, 1
	v_add3_u32 v19, v33, v19, s87
	v_bfe_u32 v22, v35, 16, 1
	v_lshrrev_b32_e32 v19, 16, v19
	v_add3_u32 v22, v35, v22, s87
	v_and_or_b32 v22, v22, s90, v19
	v_bfe_u32 v19, v37, 16, 1
	v_add3_u32 v19, v37, v19, s87
	v_bfe_u32 v23, v39, 16, 1
	v_lshrrev_b32_e32 v19, 16, v19
	v_add3_u32 v23, v39, v23, s87
	v_and_or_b32 v23, v23, s90, v19
	v_or_b32_e32 v19, s4, v15
	v_lshlrev_b32_e32 v24, 7, v19
	v_mov_b32_e32 v25, v2
	ds_read2_b32 v[26:27], v10 offset0:48 offset1:56
	v_lshl_add_u64 v[24:25], v[8:9], 0, v[24:25]
	global_store_dwordx4 v[24:25], v[20:23], off nt
	ds_read2_b32 v[24:25], v10 offset0:113 offset1:121
	ds_read2_b32 v[28:29], v10 offset0:178 offset1:186
	ds_read2_b32 v[30:31], v10 offset0:243 offset1:251
	s_waitcnt lgkmcnt(3)
	v_bfe_u32 v19, v26, 16, 1
	v_add3_u32 v19, v26, v19, s87
	s_waitcnt lgkmcnt(2)
	v_bfe_u32 v20, v24, 16, 1
	ds_read2_b32 v[32:33], v42 offset0:52 offset1:60
	v_lshrrev_b32_e32 v19, 16, v19
	v_add3_u32 v20, v24, v20, s87
	ds_read2_b32 v[34:35], v42 offset0:117 offset1:125
	v_and_or_b32 v20, v20, s90, v19
	s_waitcnt lgkmcnt(3)
	v_bfe_u32 v19, v28, 16, 1
	v_add3_u32 v19, v28, v19, s87
	s_waitcnt lgkmcnt(2)
	v_bfe_u32 v21, v30, 16, 1
	ds_read2_b32 v[36:37], v42 offset0:182 offset1:190
	v_lshrrev_b32_e32 v19, 16, v19
	v_add3_u32 v21, v30, v21, s87
	ds_read2_b32 v[38:39], v42 offset0:247 offset1:255
	v_and_or_b32 v21, v21, s90, v19
	s_waitcnt lgkmcnt(3)
	v_bfe_u32 v19, v32, 16, 1
	v_add3_u32 v19, v32, v19, s87
	s_waitcnt lgkmcnt(2)
	v_bfe_u32 v22, v34, 16, 1
	v_lshrrev_b32_e32 v19, 16, v19
	v_add3_u32 v22, v34, v22, s87
	v_and_or_b32 v22, v22, s90, v19
	s_waitcnt lgkmcnt(1)
	v_bfe_u32 v19, v36, 16, 1
	v_add3_u32 v19, v36, v19, s87
	s_waitcnt lgkmcnt(0)
	v_bfe_u32 v23, v38, 16, 1
	v_lshrrev_b32_e32 v19, 16, v19
	v_add3_u32 v23, v38, v23, s87
	v_and_or_b32 v23, v23, s90, v19
	v_or_b32_e32 v19, s4, v16
	v_lshlrev_b32_e32 v40, 7, v19
	v_mov_b32_e32 v41, v2
	v_lshl_add_u64 v[40:41], v[8:9], 0, v[40:41]
	v_bfe_u32 v19, v27, 16, 1
	global_store_dwordx4 v[40:41], v[20:23], off nt
	v_add3_u32 v19, v27, v19, s87
	v_lshrrev_b32_e32 v19, 16, v19
	v_bfe_u32 v20, v25, 16, 1
	v_add3_u32 v20, v25, v20, s87
	v_and_or_b32 v20, v20, s90, v19
	v_bfe_u32 v19, v29, 16, 1
	v_add3_u32 v19, v29, v19, s87
	v_bfe_u32 v21, v31, 16, 1
	v_lshrrev_b32_e32 v19, 16, v19
	v_add3_u32 v21, v31, v21, s87
	v_and_or_b32 v21, v21, s90, v19
	v_bfe_u32 v19, v33, 16, 1
	v_add3_u32 v19, v33, v19, s87
	v_bfe_u32 v22, v35, 16, 1
	v_lshrrev_b32_e32 v19, 16, v19
	v_add3_u32 v22, v35, v22, s87
	v_and_or_b32 v22, v22, s90, v19
	v_bfe_u32 v19, v37, 16, 1
	v_add3_u32 v19, v37, v19, s87
	v_bfe_u32 v23, v39, 16, 1
	v_lshrrev_b32_e32 v19, 16, v19
	v_add3_u32 v23, v39, v23, s87
	v_and_or_b32 v23, v23, s90, v19
	v_or_b32_e32 v19, s4, v17
	v_lshlrev_b32_e32 v24, 7, v19
	v_mov_b32_e32 v25, v2
	v_lshl_add_u64 v[8:9], v[8:9], 0, v[24:25]
	global_store_dwordx4 v[8:9], v[20:23], off nt
	s_waitcnt lgkmcnt(0)
	s_branch .LBB0_359
